# attention: 4-slot DMA ring; waves 0-3 barrier after the MFMA phase, waves 4-7 barrier between QK and PV (half-phase offset so one half's QK pairs with the other's PV); nt x stores
# speedup vs baseline: 1.0044x; 1.0013x over previous
; __device__ __forceinline__ void finishSM(f32x16& p0, f32x16& p1, float alpha, float& l_reg, bf16x8& pa0, bf16x8& pa1, bf16x8& pa2, bf16x8& pa3) {
;   for (int r = 0; r < 16; ++r) p1[r] = __builtin_amdgcn_exp2f(p1[r]);
;   float ps = 0; for (int r = 0; r < 16; ++r) ps += p0[r]; for (int r = 0; r < 16; ++r) ps += p1[r];
;   { auto rr = __builtin_amdgcn_permlane32_swap(__float_as_uint(ps), __float_as_uint(ps), false, false);
;     ps = __uint_as_float(rr[0]) + __uint_as_float(rr[1]); }
;   l_reg = l_reg * alpha + ps;
;     ...
;   PK4(p0, 0, pa0); PK4(p0, 8, pa1); PK4(p1, 0, pa2); PK4(p1, 8, pa3);
;     ...
; }
; __device__ __forceinline__ void qkt(f32x16& p0, f32x16& p1, const bf16* Ks, const bf16x8* qr, int r32, int hi) {
;   p0 = f32x16{}; p1 = f32x16{};
;   for (int d0 = 0; d0 < 8; ++d0) { int cb = (d0 * 16 + hi * 8) * 2;
;     bf16x8 b0 = *reinterpret_cast<const bf16x8*>((const char*)Ks + KSWZ(r32, cb));
;     bf16x8 b1 = *reinterpret_cast<const bf16x8*>((const char*)Ks + KSWZ(32 + r32, cb));
;     p0 = __builtin_amdgcn_mfma_f32_32x32x16_bf16(b0, qr[d0], p0, 0, 0, 0);
;     p1 = __builtin_amdgcn_mfma_f32_32x32x16_bf16(b1, qr[d0], p1, 0, 0, 0); }
; }
; __device__ __forceinline__ int v_st(int k, int c) { const int kk = (k & ~0xC) | ((k & 4) << 1) | ((k & 8) >> 1); return ((kk >> 3) * 4 + (c >> 5)) * 512 + ((kk & 7) * 32 + (c & 31)) * 2; }
; __device__ __forceinline__ int v_rd_base(int lane) { return ((lane & 3) << 3) | (((lane >> 2) & 3) << 6) | (((lane >> 4) & 1) << 5) | (((lane >> 5) & 1) << 8); }
; template <int OFF> __device__ __forceinline__ s16x4 tr_read(int vb) {
;   s16x4 r; asm volatile("ds_read_b64_tr_b16 %0, %1 offset:%2" : "=&v"(r) : "v"(vb), "i"(OFF) : "memory"); return r;
; }
; template <int D0> __device__ __forceinline__ void pv_one(f32x16& od, int vb, bf16x8 pa0, bf16x8 pa1, bf16x8 pa2, bf16x8 pa3) {
;   const s16x4 l0 = tr_read<v_rd_off(D0, 0, 0)>(vb), h0 = tr_read<v_rd_off(D0, 0, 1)>(vb), l1 = tr_read<v_rd_off(D0, 1, 0)>(vb), h1 = tr_read<v_rd_off(D0, 1, 1)>(vb);
;   const s16x4 l2 = tr_read<v_rd_off(D0, 2, 0)>(vb), h2 = tr_read<v_rd_off(D0, 2, 1)>(vb), l3 = tr_read<v_rd_off(D0, 3, 0)>(vb), h3 = tr_read<v_rd_off(D0, 3, 1)>(vb);
;   asm volatile("s_waitcnt lgkmcnt(0)" ::: "memory"); SBAR();
;     ...
;   od = __builtin_amdgcn_mfma_f32_32x32x16_bf16(pa0, PK(l0, h0), od, 0, 0, 0);
;   od = __builtin_amdgcn_mfma_f32_32x32x16_bf16(pa1, PK(l1, h1), od, 0, 0, 0);
.LBB0_76:
	ds_read_b128 v[64:67], v193 offset:49152
	ds_read_b128 v[68:71], v193 offset:57344
	ds_read_b128 v[222:225], v198 offset:49152
	ds_read_b128 v[226:229], v198 offset:57344
	v_add_f32_e32 v160, 0, v161
	v_add_f32_e32 v160, v175, v160
	s_waitcnt lgkmcnt(3)
	v_mfma_f32_32x32x16_bf16 v[80:95], v[64:67], v[112:115], 0
	v_add_f32_e32 v160, v162, v160
	v_add_f32_e32 v160, v205, v160
	v_add_f32_e32 v160, v174, v160
	v_add_f32_e32 v160, v214, v160
	v_add_f32_e32 v160, v163, v160
	v_add_f32_e32 v160, v173, v160
	v_add_f32_e32 v160, v164, v160
	s_waitcnt lgkmcnt(2)
	v_mfma_f32_32x32x16_bf16 v[64:79], v[68:71], v[112:115], 0
	v_add_f32_e32 v160, v171, v160
	v_add_f32_e32 v160, v165, v160
	v_add_f32_e32 v160, v172, v160
	v_exp_f32_e32 v158, v158
	v_add_f32_e32 v160, v166, v160
	v_exp_f32_e32 v159, v159
	v_add_f32_e32 v160, v169, v160
	s_waitcnt lgkmcnt(1)
	v_mfma_f32_32x32x16_bf16 v[80:95], v[222:225], v[108:111], v[80:95]
	v_exp_f32_e32 v156, v156
	v_add_f32_e32 v160, v167, v160
	v_exp_f32_e32 v157, v157
	v_add_f32_e32 v160, v170, v160
	v_exp_f32_e32 v152, v152
	v_add_f32_e32 v160, v158, v160
	v_exp_f32_e32 v153, v153
	s_waitcnt lgkmcnt(0)
	v_mfma_f32_32x32x16_bf16 v[64:79], v[226:229], v[108:111], v[64:79]
	ds_read_b128 v[222:225], v197 offset:49152
	ds_read_b128 v[226:229], v197 offset:57344
	v_add_f32_e32 v160, v159, v160
	v_exp_f32_e32 v148, v148
	v_add_f32_e32 v160, v156, v160
	v_exp_f32_e32 v149, v149
	v_add_f32_e32 v160, v157, v160
	v_exp_f32_e32 v146, v146
	s_waitcnt lgkmcnt(1)
	v_mfma_f32_32x32x16_bf16 v[80:95], v[222:225], v[120:123], v[80:95]
	v_add_f32_e32 v160, v152, v160
	v_exp_f32_e32 v147, v147
	v_add_f32_e32 v160, v153, v160
	v_exp_f32_e32 v154, v154
	v_add_f32_e32 v160, v148, v160
	v_exp_f32_e32 v155, v155
	v_add_f32_e32 v160, v149, v160
	s_waitcnt lgkmcnt(0)
	v_mfma_f32_32x32x16_bf16 v[64:79], v[226:229], v[120:123], v[64:79]
	ds_read_b128 v[222:225], v196 offset:49152
	ds_read_b128 v[226:229], v196 offset:57344
	v_exp_f32_e32 v150, v150
	v_add_f32_e32 v160, v146, v160
	v_exp_f32_e32 v151, v151
	v_add_f32_e32 v160, v147, v160
	v_exp_f32_e32 v144, v144
	v_add_f32_e32 v160, v154, v160
	s_waitcnt lgkmcnt(1)
	v_mfma_f32_32x32x16_bf16 v[80:95], v[222:225], v[124:127], v[80:95]
	v_exp_f32_e32 v145, v145
	v_add_f32_e32 v160, v155, v160
	v_add_f32_e32 v160, v150, v160
	v_add_f32_e32 v160, v151, v160
	v_add_f32_e32 v160, v144, v160
	v_add_f32_e32 v202, v145, v160
	v_mov_b32_e32 v203, v202
	s_waitcnt lgkmcnt(0)
	v_mfma_f32_32x32x16_bf16 v[64:79], v[226:229], v[124:127], v[64:79]
	ds_read_b128 v[222:225], v194 offset:49152
	ds_read_b128 v[226:229], v194 offset:57344
	v_permlane32_swap_b32_e32 v202, v203
	s_waitcnt lgkmcnt(1)
	v_mfma_f32_32x32x16_bf16 v[80:95], v[222:225], v[116:119], v[80:95]
	s_waitcnt lgkmcnt(0)
	v_mfma_f32_32x32x16_bf16 v[64:79], v[226:229], v[116:119], v[64:79]
	ds_read_b128 v[222:225], v195 offset:49152
	ds_read_b128 v[226:229], v195 offset:57344
	s_waitcnt lgkmcnt(1)
	v_mfma_f32_32x32x16_bf16 v[80:95], v[222:225], v[104:107], v[80:95]
	s_waitcnt lgkmcnt(0)
	v_mfma_f32_32x32x16_bf16 v[64:79], v[226:229], v[104:107], v[64:79]
	ds_read_b128 v[222:225], v200 offset:49152
	ds_read_b128 v[226:229], v200 offset:57344
	s_waitcnt lgkmcnt(1)
	v_mfma_f32_32x32x16_bf16 v[80:95], v[222:225], v[100:103], v[80:95]
	s_waitcnt lgkmcnt(0)
	v_mfma_f32_32x32x16_bf16 v[64:79], v[226:229], v[100:103], v[64:79]
	ds_read_b128 v[222:225], v199 offset:49152
	ds_read_b128 v[226:229], v199 offset:57344
	v_cvt_pk_bf16_f32 v160, v161, v175
	v_cvt_pk_bf16_f32 v161, v162, v205
	v_cvt_pk_bf16_f32 v162, v174, v214
	v_cvt_pk_bf16_f32 v163, v163, v173
	v_cvt_pk_bf16_f32 v164, v164, v171
	v_cvt_pk_bf16_f32 v165, v165, v172
	s_waitcnt lgkmcnt(1)
	v_mfma_f32_32x32x16_bf16 v[80:95], v[222:225], v[96:99], v[80:95]
	v_cvt_pk_bf16_f32 v166, v166, v169
	v_cvt_pk_bf16_f32 v167, v167, v170
	v_cvt_pk_bf16_f32 v170, v158, v159
	v_cvt_pk_bf16_f32 v171, v156, v157
	v_cvt_pk_bf16_f32 v172, v152, v153
	v_cvt_pk_bf16_f32 v173, v148, v149
	v_cvt_pk_bf16_f32 v204, v146, v147
	s_waitcnt lgkmcnt(0)
	v_mfma_f32_32x32x16_bf16 v[64:79], v[226:229], v[96:99], v[64:79]
	v_cvt_pk_bf16_f32 v205, v154, v155
	v_cvt_pk_bf16_f32 v206, v150, v151
	v_permlane32_swap_b32_e32 v160, v162
	v_cvt_pk_bf16_f32 v207, v144, v145
	v_permlane32_swap_b32_e32 v204, v206
	v_permlane32_swap_b32_e32 v161, v163
	v_permlane32_swap_b32_e32 v164, v166
	v_permlane32_swap_b32_e32 v165, v167
	v_permlane32_swap_b32_e32 v170, v172
	v_permlane32_swap_b32_e32 v171, v173
	v_permlane32_swap_b32_e32 v205, v207
	s_cmp_ge_u32 s5, 0x2000
	s_cbranch_scc0 .Latt_nb_m1
	s_waitcnt vmcnt(4)
	s_barrier
; #define SBAR() __builtin_amdgcn_sched_barrier(0)
; __device__ __forceinline__ void partialSM(f32x16& p0, f32x16& p1, float& m_reg, float& mn, float& alpha) {
;   constexpr float C = SCALE * 1.4426950408889634f;
;   float pmax = p0[0]; for (int r = 1; r < 16; ++r) pmax = fmaxf(pmax, p0[r]); for (int r = 0; r < 16; ++r) pmax = fmaxf(pmax, p1[r]);
;   { auto rr = __builtin_amdgcn_permlane32_swap(__float_as_uint(pmax), __float_as_uint(pmax), false, false);
;     pmax = fmaxf(__uint_as_float(rr[0]), __uint_as_float(rr[1])); }
;   if (__builtin_expect(__all(pmax - m_reg <= THR / SCALE), 1)) { mn = m_reg; alpha = 1.f; }
;   else { mn = fmaxf(m_reg, pmax); alpha = __builtin_amdgcn_exp2f((m_reg - mn) * C); m_reg = mn; }
; template <int D0> __device__ __forceinline__ void pv_one(f32x16& od, int vb, bf16x8 pa0, bf16x8 pa1, bf16x8 pa2, bf16x8 pa3) {
;   const s16x4 l0 = tr_read<v_rd_off(D0, 0, 0)>(vb), h0 = tr_read<v_rd_off(D0, 0, 1)>(vb), l1 = tr_read<v_rd_off(D0, 1, 0)>(vb), h1 = tr_read<v_rd_off(D0, 1, 1)>(vb);
;   const s16x4 l2 = tr_read<v_rd_off(D0, 2, 0)>(vb), h2 = tr_read<v_rd_off(D0, 2, 1)>(vb), l3 = tr_read<v_rd_off(D0, 3, 0)>(vb), h3 = tr_read<v_rd_off(D0, 3, 1)>(vb);
;   asm volatile("s_waitcnt lgkmcnt(0)" ::: "memory"); SBAR();
;     ...
;   od = __builtin_amdgcn_mfma_f32_32x32x16_bf16(pa0, PK(l0, h0), od, 0, 0, 0);
;   od = __builtin_amdgcn_mfma_f32_32x32x16_bf16(pa1, PK(l1, h1), od, 0, 0, 0);
;   od = __builtin_amdgcn_mfma_f32_32x32x16_bf16(pa2, PK(l2, h2), od, 0, 0, 0);
;   od = __builtin_amdgcn_mfma_f32_32x32x16_bf16(pa3, PK(l3, h3), od, 0, 0, 0);
;     ...
; }
; __device__ __forceinline__ void pv_d0(f32x16* o, int vb, bf16x8 pa0, bf16x8 pa1, bf16x8 pa2, bf16x8 pa3) {
;   pv_one<0>(o[0], vb, pa0, pa1, pa2, pa3); pv_one<1>(o[1], vb, pa0, pa1, pa2, pa3); pv_one<2>(o[2], vb, pa0, pa1, pa2, pa3); pv_one<3>(o[3], vb, pa0, pa1, pa2, pa3);
.Latt_nb_m1:
	ds_read_b64_tr_b16 v[222:223], v188 offset:0
	ds_read_b64_tr_b16 v[224:225], v188 offset:0x800
	ds_read_b64_tr_b16 v[226:227], v188 offset:0x1000
	ds_read_b64_tr_b16 v[228:229], v188 offset:0x1800
	ds_read_b64_tr_b16 v[230:231], v188 offset:0x2000
	ds_read_b64_tr_b16 v[232:233], v188 offset:0x2800
	ds_read_b64_tr_b16 v[234:235], v188 offset:0x3000
	ds_read_b64_tr_b16 v[236:237], v188 offset:0x3800
	s_waitcnt lgkmcnt(0)
	s_nop 0
	v_mfma_f32_32x32x16_bf16 v[0:15], v[160:163], v[222:225], v[0:15]
	ds_read_b64_tr_b16 v[222:223], v188 offset:0x200
	ds_read_b64_tr_b16 v[224:225], v188 offset:0xa00
	v_mfma_f32_32x32x16_bf16 v[0:15], v[164:167], v[226:229], v[0:15]
	ds_read_b64_tr_b16 v[226:227], v188 offset:0x1200
	ds_read_b64_tr_b16 v[228:229], v188 offset:0x1a00
	v_mfma_f32_32x32x16_bf16 v[0:15], v[170:173], v[230:233], v[0:15]
	ds_read_b64_tr_b16 v[230:231], v188 offset:0x2200
	ds_read_b64_tr_b16 v[232:233], v188 offset:0x2a00
	v_mfma_f32_32x32x16_bf16 v[0:15], v[204:207], v[234:237], v[0:15]
	ds_read_b64_tr_b16 v[234:235], v188 offset:0x3200
	ds_read_b64_tr_b16 v[236:237], v188 offset:0x3a00
	s_waitcnt lgkmcnt(0)
	v_mfma_f32_32x32x16_bf16 v[48:63], v[160:163], v[222:225], v[48:63]
	ds_read_b64_tr_b16 v[222:223], v188 offset:0x400
	ds_read_b64_tr_b16 v[224:225], v188 offset:0xc00
	v_mfma_f32_32x32x16_bf16 v[48:63], v[164:167], v[226:229], v[48:63]
	ds_read_b64_tr_b16 v[226:227], v188 offset:0x1400
	ds_read_b64_tr_b16 v[228:229], v188 offset:0x1c00
	v_mfma_f32_32x32x16_bf16 v[48:63], v[170:173], v[230:233], v[48:63]
	ds_read_b64_tr_b16 v[230:231], v188 offset:0x2400
	ds_read_b64_tr_b16 v[232:233], v188 offset:0x2c00
	v_mfma_f32_32x32x16_bf16 v[48:63], v[204:207], v[234:237], v[48:63]
	ds_read_b64_tr_b16 v[234:235], v188 offset:0x3400
	ds_read_b64_tr_b16 v[236:237], v188 offset:0x3c00
	s_waitcnt lgkmcnt(0)
	v_mfma_f32_32x32x16_bf16 v[32:47], v[160:163], v[222:225], v[32:47]
	ds_read_b64_tr_b16 v[222:223], v188 offset:0x600
	ds_read_b64_tr_b16 v[224:225], v188 offset:0xe00
	v_mfma_f32_32x32x16_bf16 v[32:47], v[164:167], v[226:229], v[32:47]
	ds_read_b64_tr_b16 v[226:227], v188 offset:0x1600
	ds_read_b64_tr_b16 v[228:229], v188 offset:0x1e00
	v_mfma_f32_32x32x16_bf16 v[32:47], v[170:173], v[230:233], v[32:47]
	ds_read_b64_tr_b16 v[230:231], v188 offset:0x2600
	ds_read_b64_tr_b16 v[232:233], v188 offset:0x2e00
	v_mfma_f32_32x32x16_bf16 v[32:47], v[204:207], v[234:237], v[32:47]
	ds_read_b64_tr_b16 v[234:235], v188 offset:0x3600
	ds_read_b64_tr_b16 v[236:237], v188 offset:0x3e00
	s_waitcnt lgkmcnt(0)
	v_mfma_f32_32x32x16_bf16 v[16:31], v[160:163], v[222:225], v[16:31]
	v_max_f32_e32 v160, v81, v81
	v_max_f32_e32 v161, v80, v80
	v_max_f32_e32 v160, v161, v160
	v_max3_f32 v160, v160, v82, v83
	v_max3_f32 v160, v160, v84, v85
	v_max3_f32 v160, v160, v86, v87
	v_max3_f32 v160, v160, v88, v89
	v_max3_f32 v160, v160, v90, v91
	v_max3_f32 v160, v160, v92, v93
	v_mfma_f32_32x32x16_bf16 v[16:31], v[164:167], v[226:229], v[16:31]
	v_max3_f32 v160, v160, v94, v95
	v_max3_f32 v160, v160, v64, v65
	v_max3_f32 v160, v160, v66, v67
	v_max3_f32 v160, v160, v68, v69
	v_max3_f32 v160, v160, v70, v71
	v_max3_f32 v160, v160, v72, v73
	v_max3_f32 v160, v160, v74, v75
	v_max3_f32 v160, v160, v76, v77
	v_mfma_f32_32x32x16_bf16 v[16:31], v[170:173], v[230:233], v[16:31]
	v_max3_f32 v160, v160, v78, v79
	v_mov_b32_e32 v161, v160
	s_nop 1
	v_permlane32_swap_b32_e32 v160, v161
	v_max_f32_e32 v161, v161, v161
	v_max_f32_e32 v160, v160, v160
	v_max_f32_e32 v160, v160, v161
	v_sub_f32_e32 v161, v160, v168
	v_cmp_ge_f32_e32 vcc, s4, v161
	v_max_f32_e32 v161, v168, v168
	v_max_f32_e32 v160, v161, v160
	v_mfma_f32_32x32x16_bf16 v[16:31], v[204:207], v[234:237], v[16:31]
	v_sub_f32_e32 v161, v168, v160
	v_mul_f32_e32 v161, 0x3e0293ee, v161
	v_exp_f32_e32 v161, v161
	s_cmp_eq_u64 vcc, exec
	s_cselect_b64 s[0:1], -1, 0
	s_cmp_ge_u32 s5, 0x2000
	s_cbranch_scc1 .Latt_nb_p0a
	s_waitcnt vmcnt(4)
	s_barrier

; #define SWAIT() do { if constexpr (SDEPTH == 2) asm volatile("s_waitcnt vmcnt(4)" ::: "memory"); else asm volatile("s_waitcnt vmcnt(0)" ::: "memory"); } while (0)
; #define RESC(a) do { if (__any((a) < 1.f)) { if (hi == 0) al_l[r32] = (a); asm volatile("s_waitcnt lgkmcnt(0)" ::: "memory"); \
;     for (int d = 0; d < 4; ++d) for (int r = 0; r < 16; ++r) o[d][r] *= al_l[crow(r, hi)]; } } while (0)
; template <typename TQ>
; __device__ __forceinline__ void attn_dense_body(const TQ* __restrict__ Qb, const bf16* __restrict__ Kh, const bf16* __restrict__ Vh,
;                                                 unsigned short* __restrict__ Ob, int seq, char* lds) {
;     ...
;     pv_d0(o, vb0 + (int)SHM_V, pa0, pa1, pa2, pa3); partialSM(pA0, pA1, m_reg, mnA, alA);
;     __syncthreads(); SWAIT(); SWRITE(1, SO);
;     RESC(alA); __syncthreads();
.LBB0_82:
	s_cmp_ge_u32 s5, 0x2000
	s_cbranch_scc0 .Latt_nb_m2
	s_waitcnt vmcnt(4)
	s_barrier
